# remove grid barrier between P0 and P1: GEMV partials and small vectors published with write-through stores + arrival counter, P1 table loads sc1
# speedup vs baseline: 1.0200x; 1.0200x over previous
.LBB0_13:
	s_lshr_b32 s28, s29, 6
	s_cmp_lt_i32 s26, 1
	s_cselect_b64 s[4:5], -1, 0
	s_cmp_gt_i32 s27, 0
	s_cselect_b64 s[6:7], -1, 0
	s_and_b64 s[12:13], s[4:5], s[6:7]
	s_andn2_b64 vcc, exec, s[12:13]
	s_cbranch_vccnz .LBB0_68
	s_load_dwordx4 s[8:11], s[0:1], 0x8
	s_load_dwordx2 s[16:17], s[0:1], 0x20
	s_lshl_b32 s31, s2, 9
	s_lshl_b32 s30, s3, 9
	v_bitop3_b32 v3, s31, v0, s31 bitop3:3
	v_add_u32_e32 v2, s30, v3
	s_mov_b32 s4, 0xb580
	v_and_b32_e32 v1, 63, v0
	v_cmp_gt_i32_e32 vcc, s4, v2
	s_mov_b64 s[14:15], s[24:25]
	s_and_saveexec_b64 s[4:5], vcc
	s_cbranch_execz .LBB0_16
	v_ashrrev_i32_e32 v4, 6, v2
	v_ashrrev_i32_e32 v5, 31, v4
	s_add_u32 s6, s0, 0x58
	s_movk_i32 s41, 0x100
	v_and_b32_e32 v3, 63, v3
	v_lshl_add_u64 v[4:5], v[4:5], 3, s[0:1]
	v_add_u32_e32 v6, 0xffffff00, v2
	s_addc_u32 s7, s1, 0
	v_cmp_gt_i32_e32 vcc, s41, v2
	v_lshl_add_u64 v[4:5], v[4:5], 0, 56
	s_add_u32 s18, s0, 0x68
	v_cndmask_b32_e32 v3, v6, v3, vcc
	v_mov_b32_e32 v6, s6
	s_addc_u32 s19, s1, 0
	s_movk_i32 s42, 0x180
	v_cndmask_b32_e32 v4, v6, v4, vcc
	v_mov_b32_e32 v6, s7
	s_add_u32 s20, s0, 0x70
	v_cndmask_b32_e32 v5, v6, v5, vcc
	v_cmp_gt_i32_e32 vcc, s42, v2
	v_mov_b32_e32 v6, s19
	v_add_u32_e32 v7, 0xfffffe80, v2
	s_addc_u32 s21, s1, 0
	s_movk_i32 s6, 0x580
	v_cndmask_b32_e32 v5, v6, v5, vcc
	v_mov_b32_e32 v6, s18
	s_add_u32 s22, s0, 0x78
	v_cndmask_b32_e32 v3, v7, v3, vcc
	v_cndmask_b32_e32 v4, v6, v4, vcc
	v_cmp_gt_i32_e32 vcc, s6, v2
	v_mov_b32_e32 v6, s20
	v_add_u32_e32 v8, 0xfffffa80, v2
	s_addc_u32 s23, s1, 0
	s_movk_i32 s7, 0x980
	v_cndmask_b32_e32 v4, v6, v4, vcc
	v_mov_b32_e32 v6, s21
	s_add_u32 s34, s0, 0x88
	v_cndmask_b32_e32 v3, v8, v3, vcc
	v_cndmask_b32_e32 v5, v6, v5, vcc
	v_cmp_gt_i32_e32 vcc, s7, v2
	v_mov_b32_e32 v6, s23
	v_add_u32_e32 v9, 0xfffff680, v2
	s_addc_u32 s35, s1, 0
	s_movk_i32 s6, 0xd80
	v_cndmask_b32_e32 v5, v6, v5, vcc
	v_mov_b32_e32 v6, s22
	s_add_u32 s36, s0, 0x98
	v_cndmask_b32_e32 v3, v9, v3, vcc
	v_cndmask_b32_e32 v4, v6, v4, vcc
	v_cmp_gt_i32_e32 vcc, s6, v2
	v_mov_b32_e32 v6, s34
	v_add_u32_e32 v10, 0xfffff280, v2
	s_addc_u32 s37, s1, 0
	s_movk_i32 s7, 0x1180
	v_cndmask_b32_e32 v4, v6, v4, vcc
	v_mov_b32_e32 v6, s35
	v_cndmask_b32_e32 v3, v10, v3, vcc
	v_cndmask_b32_e32 v5, v6, v5, vcc
	v_cmp_gt_i32_e32 vcc, s7, v2
	v_mov_b32_e32 v6, s37
	v_add_u32_e32 v11, 0xffffee80, v2
	s_add_u32 s38, s0, 24
	s_movk_i32 s6, 0x1980
	v_cndmask_b32_e32 v5, v6, v5, vcc
	v_mov_b32_e32 v6, s36
	s_addc_u32 s39, s1, 0
	v_cndmask_b32_e32 v3, v11, v3, vcc
	v_cndmask_b32_e32 v4, v6, v4, vcc
	v_cmp_gt_i32_e32 vcc, s6, v2
	v_mov_b32_e32 v6, s38
	v_add_u32_e32 v12, 0xffffe680, v2
	s_movk_i32 s40, 0x3980
	v_cndmask_b32_e32 v8, v6, v4, vcc
	v_mov_b32_e32 v4, s39
	v_cndmask_b32_e32 v3, v12, v3, vcc
	v_cndmask_b32_e32 v9, v4, v5, vcc
	v_mov_b32_e32 v4, 0xffffc680
	v_mov_b32_e32 v5, 0xffffde80
	v_cmp_gt_u32_e32 vcc, s40, v2
	s_movk_i32 s7, 0x2180
	s_nop 0
	v_cndmask_b32_e32 v4, v4, v5, vcc
	v_add_u32_e32 v10, v2, v4
	v_mov_b32_e32 v4, 0x60
	v_cndmask_b32_e64 v4, v4, 40, vcc
	v_mov_b32_e32 v5, 0
	v_lshl_add_u64 v[6:7], s[0:1], 0, v[4:5]
	v_cmp_gt_i32_e32 vcc, s7, v2
	s_nop 1
	v_cndmask_b32_e32 v7, v7, v9, vcc
	v_cndmask_b32_e32 v6, v6, v8, vcc
	global_load_dwordx2 v[6:7], v[6:7], off
	v_cndmask_b32_e32 v4, v10, v3, vcc
	v_ashrrev_i32_e32 v3, 31, v2
	v_lshl_add_u64 v[2:3], v[2:3], 2, s[14:15]
	v_add_co_u32_e32 v2, vcc, 0x2b00000, v2
	s_waitcnt vmcnt(0)
	v_lshl_add_u64 v[4:5], v[4:5], 2, v[6:7]
	global_load_dword v4, v[4:5], off
	v_addc_co_u32_e32 v3, vcc, 0, v3, vcc
	s_waitcnt vmcnt(0)
	flat_store_dword v[2:3], v4 sc1

.LBB0_20:
	s_or_b64 exec, exec, s[22:23]
	s_lshl_b32 s6, s42, 12
	s_sub_i32 s6, s35, s6
	v_add_u32_e32 v2, s6, v12
	v_ashrrev_i32_e32 v3, 31, v2
	s_waitcnt lgkmcnt(0)
	v_lshl_add_u64 v[8:9], v[2:3], 2, s[16:17]
	v_mad_i64_i32 v[2:3], s[22:23], s43, v47, v[8:9]
	s_or_b32 s7, s43, 1
	global_load_dwordx4 v[2:5], v[2:3], off nt
	v_mad_i64_i32 v[50:51], s[22:23], s7, v47, v[8:9]
	s_or_b32 s7, s43, 2
	global_load_dwordx4 v[50:53], v[50:51], off nt
	v_mad_i64_i32 v[54:55], s[22:23], s7, v47, v[8:9]
	s_or_b32 s7, s43, 3
	global_load_dwordx4 v[54:57], v[54:55], off nt
	v_mad_i64_i32 v[58:59], s[22:23], s7, v47, v[8:9]
	global_load_dwordx4 v[58:61], v[58:59], off nt
	s_or_b32 s7, s43, 4
	v_mad_i64_i32 v[62:63], s[22:23], s7, v47, v[8:9]
	s_or_b32 s7, s43, 5
	global_load_dwordx4 v[62:65], v[62:63], off nt
	v_mad_i64_i32 v[66:67], s[22:23], s7, v47, v[8:9]
	s_or_b32 s7, s43, 6
	global_load_dwordx4 v[66:69], v[66:67], off nt
	v_mad_i64_i32 v[70:71], s[22:23], s7, v47, v[8:9]
	global_load_dwordx4 v[70:73], v[70:71], off nt
	s_or_b32 s7, s43, 7
	v_mad_i64_i32 v[74:75], s[22:23], s7, v47, v[8:9]
	s_or_b32 s7, s43, 8
	global_load_dwordx4 v[74:77], v[74:75], off nt
	v_mad_i64_i32 v[78:79], s[22:23], s7, v47, v[8:9]
	global_load_dwordx4 v[78:81], v[78:79], off nt
	s_or_b32 s7, s43, 9
	v_mad_i64_i32 v[82:83], s[22:23], s7, v47, v[8:9]
	global_load_dwordx4 v[82:85], v[82:83], off nt
	s_or_b32 s7, s43, 10
	v_mad_i64_i32 v[86:87], s[22:23], s7, v47, v[8:9]
	global_load_dwordx4 v[86:89], v[86:87], off nt
	s_or_b32 s7, s43, 11
	v_mad_i64_i32 v[90:91], s[22:23], s7, v47, v[8:9]
	global_load_dwordx4 v[90:93], v[90:91], off nt
	s_or_b32 s7, s43, 12
	v_mad_i64_i32 v[94:95], s[22:23], s7, v47, v[8:9]
	s_or_b32 s44, s43, 13
	global_load_dwordx4 v[94:97], v[94:95], off nt
	s_or_b32 s45, s43, 14
	v_mad_i64_i32 v[126:127], s[22:23], s44, v47, v[8:9]
	v_mad_i64_i32 v[128:129], s[22:23], s45, v47, v[8:9]
	global_load_dwordx4 v[98:101], v[126:127], off nt
	global_load_dwordx4 v[102:105], v[128:129], off nt
	ds_bpermute_b32 v106, v13, v49
	ds_bpermute_b32 v108, v13, v48
	ds_bpermute_b32 v110, v14, v49
	ds_bpermute_b32 v112, v14, v48
	ds_bpermute_b32 v114, v15, v49
	ds_bpermute_b32 v116, v15, v48
	ds_bpermute_b32 v118, v16, v49
	ds_bpermute_b32 v120, v16, v48
	ds_bpermute_b32 v122, v17, v49
	ds_bpermute_b32 v124, v17, v48
	s_or_b32 s7, s43, 15
	s_add_i32 s41, s41, s3
	s_add_i32 s35, s35, s36
	s_waitcnt vmcnt(0) lgkmcnt(0)
	v_pk_fma_f32 v[126:127], v[4:5], v[106:107], 0 op_sel_hi:[1,0,0]
	v_pk_fma_f32 v[106:107], v[2:3], v[106:107], 0 op_sel_hi:[1,0,0]
	v_pk_fma_f32 v[2:3], v[2:3], v[108:109], 0 op_sel_hi:[1,0,0]
	v_pk_fma_f32 v[4:5], v[4:5], v[108:109], 0 op_sel_hi:[1,0,0]
	v_pk_fma_f32 v[106:107], v[50:51], v[110:111], v[106:107] op_sel_hi:[1,0,1]
	v_pk_fma_f32 v[2:3], v[50:51], v[112:113], v[2:3] op_sel_hi:[1,0,1]
	v_pk_fma_f32 v[108:109], v[52:53], v[110:111], v[126:127] op_sel_hi:[1,0,1]
	v_pk_fma_f32 v[4:5], v[52:53], v[112:113], v[4:5] op_sel_hi:[1,0,1]
	v_pk_fma_f32 v[52:53], v[54:55], v[114:115], v[106:107] op_sel_hi:[1,0,1]
	v_pk_fma_f32 v[2:3], v[54:55], v[116:117], v[2:3] op_sel_hi:[1,0,1]
	ds_bpermute_b32 v54, v18, v49
	v_pk_fma_f32 v[52:53], v[58:59], v[118:119], v[52:53] op_sel_hi:[1,0,1]
	v_pk_fma_f32 v[2:3], v[58:59], v[120:121], v[2:3] op_sel_hi:[1,0,1]
	ds_bpermute_b32 v58, v19, v49
	v_pk_fma_f32 v[50:51], v[56:57], v[114:115], v[108:109] op_sel_hi:[1,0,1]
	v_pk_fma_f32 v[4:5], v[56:57], v[116:117], v[4:5] op_sel_hi:[1,0,1]
	ds_bpermute_b32 v56, v18, v48
	v_pk_fma_f32 v[50:51], v[60:61], v[118:119], v[50:51] op_sel_hi:[1,0,1]
	v_pk_fma_f32 v[4:5], v[60:61], v[120:121], v[4:5] op_sel_hi:[1,0,1]
	v_pk_fma_f32 v[50:51], v[64:65], v[122:123], v[50:51] op_sel_hi:[1,0,1]
	v_pk_fma_f32 v[52:53], v[62:63], v[122:123], v[52:53] op_sel_hi:[1,0,1]
	s_waitcnt lgkmcnt(2)
	v_pk_fma_f32 v[50:51], v[68:69], v[54:55], v[50:51] op_sel_hi:[1,0,1]
	v_pk_fma_f32 v[4:5], v[64:65], v[124:125], v[4:5] op_sel_hi:[1,0,1]
	v_pk_fma_f32 v[2:3], v[62:63], v[124:125], v[2:3] op_sel_hi:[1,0,1]
	v_pk_fma_f32 v[52:53], v[66:67], v[54:55], v[52:53] op_sel_hi:[1,0,1]
	s_waitcnt lgkmcnt(1)
	v_pk_fma_f32 v[54:55], v[72:73], v[58:59], v[50:51] op_sel_hi:[1,0,1]
	v_mad_i64_i32 v[50:51], s[22:23], s7, v47, v[8:9]
	s_waitcnt lgkmcnt(0)
	v_pk_fma_f32 v[4:5], v[68:69], v[56:57], v[4:5] op_sel_hi:[1,0,1]
	v_pk_fma_f32 v[2:3], v[66:67], v[56:57], v[2:3] op_sel_hi:[1,0,1]
	v_pk_fma_f32 v[56:57], v[70:71], v[58:59], v[52:53] op_sel_hi:[1,0,1]
	global_load_dwordx4 v[50:53], v[50:51], off nt
	ds_bpermute_b32 v58, v19, v48
	ds_bpermute_b32 v60, v20, v49
	ds_bpermute_b32 v62, v21, v49
	s_or_b32 s7, s43, 16
	ds_bpermute_b32 v64, v22, v49
	s_waitcnt lgkmcnt(3)
	v_pk_fma_f32 v[4:5], v[72:73], v[58:59], v[4:5] op_sel_hi:[1,0,1]
	v_pk_fma_f32 v[2:3], v[70:71], v[58:59], v[2:3] op_sel_hi:[1,0,1]
	ds_bpermute_b32 v58, v20, v48
	s_waitcnt lgkmcnt(3)
	v_pk_fma_f32 v[54:55], v[76:77], v[60:61], v[54:55] op_sel_hi:[1,0,1]
	v_pk_fma_f32 v[56:57], v[74:75], v[60:61], v[56:57] op_sel_hi:[1,0,1]
	ds_bpermute_b32 v60, v21, v48
	ds_bpermute_b32 v66, v22, v48
	s_waitcnt lgkmcnt(2)
	v_pk_fma_f32 v[4:5], v[76:77], v[58:59], v[4:5] op_sel_hi:[1,0,1]
	v_pk_fma_f32 v[2:3], v[74:75], v[58:59], v[2:3] op_sel_hi:[1,0,1]
	v_pk_fma_f32 v[58:59], v[80:81], v[62:63], v[54:55] op_sel_hi:[1,0,1]
	v_mad_i64_i32 v[54:55], s[22:23], s7, v47, v[8:9]
	v_pk_fma_f32 v[62:63], v[78:79], v[62:63], v[56:57] op_sel_hi:[1,0,1]
	global_load_dwordx4 v[54:57], v[54:55], off nt
	s_waitcnt lgkmcnt(1)
	v_pk_fma_f32 v[4:5], v[80:81], v[60:61], v[4:5] op_sel_hi:[1,0,1]
	v_pk_fma_f32 v[2:3], v[78:79], v[60:61], v[2:3] op_sel_hi:[1,0,1]
	v_pk_fma_f32 v[58:59], v[84:85], v[64:65], v[58:59] op_sel_hi:[1,0,1]
	ds_bpermute_b32 v60, v23, v49
	v_pk_fma_f32 v[62:63], v[82:83], v[64:65], v[62:63] op_sel_hi:[1,0,1]
	ds_bpermute_b32 v64, v23, v48
	s_waitcnt lgkmcnt(2)
	v_pk_fma_f32 v[4:5], v[84:85], v[66:67], v[4:5] op_sel_hi:[1,0,1]
	v_pk_fma_f32 v[2:3], v[82:83], v[66:67], v[2:3] op_sel_hi:[1,0,1]
	s_or_b32 s7, s43, 17
	s_waitcnt lgkmcnt(1)
	v_pk_fma_f32 v[58:59], v[88:89], v[60:61], v[58:59] op_sel_hi:[1,0,1]
	v_pk_fma_f32 v[60:61], v[86:87], v[60:61], v[62:63] op_sel_hi:[1,0,1]
	s_waitcnt lgkmcnt(0)
	v_pk_fma_f32 v[62:63], v[88:89], v[64:65], v[4:5] op_sel_hi:[1,0,1]
	v_pk_fma_f32 v[64:65], v[86:87], v[64:65], v[2:3] op_sel_hi:[1,0,1]
	v_mad_i64_i32 v[2:3], s[22:23], s7, v47, v[8:9]
	global_load_dwordx4 v[2:5], v[2:3], off nt
	ds_bpermute_b32 v66, v24, v49
	ds_bpermute_b32 v68, v24, v48
	ds_bpermute_b32 v70, v25, v49
	s_or_b32 s7, s43, 18
	ds_bpermute_b32 v80, v27, v48
	s_waitcnt lgkmcnt(3)
	v_pk_fma_f32 v[58:59], v[92:93], v[66:67], v[58:59] op_sel_hi:[1,0,1]
	v_pk_fma_f32 v[60:61], v[90:91], v[66:67], v[60:61] op_sel_hi:[1,0,1]
	s_waitcnt lgkmcnt(2)
	v_pk_fma_f32 v[62:63], v[92:93], v[68:69], v[62:63] op_sel_hi:[1,0,1]
	v_pk_fma_f32 v[64:65], v[90:91], v[68:69], v[64:65] op_sel_hi:[1,0,1]
	ds_bpermute_b32 v66, v25, v48
	ds_bpermute_b32 v68, v26, v49
	s_waitcnt lgkmcnt(3)
	v_pk_fma_f32 v[58:59], v[96:97], v[70:71], v[58:59] op_sel_hi:[1,0,1]
	v_pk_fma_f32 v[60:61], v[94:95], v[70:71], v[60:61] op_sel_hi:[1,0,1]
	ds_bpermute_b32 v70, v26, v48
	s_waitcnt lgkmcnt(2)
	v_pk_fma_f32 v[62:63], v[96:97], v[66:67], v[62:63] op_sel_hi:[1,0,1]
	v_pk_fma_f32 v[64:65], v[94:95], v[66:67], v[64:65] op_sel_hi:[1,0,1]
	s_waitcnt lgkmcnt(1)
	v_pk_fma_f32 v[66:67], v[100:101], v[68:69], v[58:59] op_sel_hi:[1,0,1]
	v_mad_i64_i32 v[58:59], s[22:23], s7, v47, v[8:9]
	v_pk_fma_f32 v[72:73], v[98:99], v[68:69], v[60:61] op_sel_hi:[1,0,1]
	global_load_dwordx4 v[58:61], v[58:59], off nt
	s_waitcnt lgkmcnt(0)
	v_pk_fma_f32 v[74:75], v[100:101], v[70:71], v[62:63] op_sel_hi:[1,0,1]
	v_pk_fma_f32 v[76:77], v[98:99], v[70:71], v[64:65] op_sel_hi:[1,0,1]
	ds_bpermute_b32 v70, v27, v49
	s_or_b32 s7, s43, 19
	v_mad_i64_i32 v[62:63], s[22:23], s7, v47, v[8:9]
	global_load_dwordx4 v[62:65], v[62:63], off nt
	s_or_b32 s7, s43, 20
	s_waitcnt lgkmcnt(0)
	v_pk_fma_f32 v[78:79], v[104:105], v[70:71], v[66:67] op_sel_hi:[1,0,1]
	v_mad_i64_i32 v[66:67], s[22:23], s7, v47, v[8:9]
	s_or_b32 s7, s43, 21
	global_load_dwordx4 v[66:69], v[66:67], off nt
	v_pk_fma_f32 v[82:83], v[102:103], v[70:71], v[72:73] op_sel_hi:[1,0,1]
	v_mad_i64_i32 v[70:71], s[22:23], s7, v47, v[8:9]
	global_load_dwordx4 v[70:73], v[70:71], off nt
	ds_bpermute_b32 v88, v28, v49
	s_or_b32 s7, s43, 22
	v_pk_fma_f32 v[84:85], v[104:105], v[80:81], v[74:75] op_sel_hi:[1,0,1]
	v_mad_i64_i32 v[74:75], s[22:23], s7, v47, v[8:9]
	ds_bpermute_b32 v90, v28, v48
	v_pk_fma_f32 v[86:87], v[102:103], v[80:81], v[76:77] op_sel_hi:[1,0,1]
	global_load_dwordx4 v[74:77], v[74:75], off nt
	s_or_b32 s7, s43, 23
	s_waitcnt vmcnt(7) lgkmcnt(1)
	v_pk_fma_f32 v[92:93], v[52:53], v[88:89], v[78:79] op_sel_hi:[1,0,1]
	v_mad_i64_i32 v[78:79], s[22:23], s7, v47, v[8:9]
	s_or_b32 s7, s43, 24
	global_load_dwordx4 v[78:81], v[78:79], off nt
	s_waitcnt lgkmcnt(0)
	v_pk_fma_f32 v[96:97], v[52:53], v[90:91], v[84:85] op_sel_hi:[1,0,1]
	v_mad_i64_i32 v[52:53], s[22:23], s7, v47, v[8:9]
	v_pk_fma_f32 v[94:95], v[50:51], v[88:89], v[82:83] op_sel_hi:[1,0,1]
	global_load_dwordx4 v[82:85], v[52:53], off nt
	s_or_b32 s7, s43, 25
	v_pk_fma_f32 v[98:99], v[50:51], v[90:91], v[86:87] op_sel_hi:[1,0,1]
	v_mad_i64_i32 v[50:51], s[22:23], s7, v47, v[8:9]
	global_load_dwordx4 v[50:53], v[50:51], off nt
	ds_bpermute_b32 v90, v29, v49
	ds_bpermute_b32 v102, v29, v48
	s_or_b32 s7, s43, 26
	v_mad_i64_i32 v[86:87], s[22:23], s7, v47, v[8:9]
	global_load_dwordx4 v[86:89], v[86:87], off nt
	s_or_b32 s7, s43, 27
	s_waitcnt vmcnt(10) lgkmcnt(1)
	v_pk_fma_f32 v[100:101], v[56:57], v[90:91], v[92:93] op_sel_hi:[1,0,1]
	s_waitcnt lgkmcnt(0)
	v_pk_fma_f32 v[106:107], v[56:57], v[102:103], v[96:97] op_sel_hi:[1,0,1]
	v_mad_i64_i32 v[56:57], s[22:23], s7, v47, v[8:9]
	s_or_b32 s7, s43, 28
	v_pk_fma_f32 v[104:105], v[54:55], v[90:91], v[94:95] op_sel_hi:[1,0,1]
	global_load_dwordx4 v[90:93], v[56:57], off nt
	v_pk_fma_f32 v[108:109], v[54:55], v[102:103], v[98:99] op_sel_hi:[1,0,1]
	v_mad_i64_i32 v[54:55], s[22:23], s7, v47, v[8:9]
	global_load_dwordx4 v[54:57], v[54:55], off nt
	ds_bpermute_b32 v98, v30, v49
	s_or_b32 s7, s43, 29
	v_mad_i64_i32 v[94:95], s[22:23], s7, v47, v[8:9]
	global_load_dwordx4 v[94:97], v[94:95], off nt
	s_or_b32 s7, s43, 30
	s_waitcnt vmcnt(12) lgkmcnt(0)
	v_pk_fma_f32 v[112:113], v[4:5], v[98:99], v[100:101] op_sel_hi:[1,0,1]
	v_pk_fma_f32 v[114:115], v[2:3], v[98:99], v[104:105] op_sel_hi:[1,0,1]
	v_mad_i64_i32 v[98:99], s[22:23], s7, v47, v[8:9]
	s_or_b32 s7, s43, 31
	global_load_dwordx4 v[98:101], v[98:99], off nt
	v_mad_i64_i32 v[8:9], s[22:23], s7, v47, v[8:9]
	global_load_dwordx4 v[102:105], v[8:9], off nt
	ds_bpermute_b32 v110, v30, v48
	ds_bpermute_b32 v116, v31, v48
	s_ashr_i32 s7, s6, 31
	s_cmpk_gt_i32 s41, 0x7f
	s_waitcnt lgkmcnt(1)
	v_pk_fma_f32 v[4:5], v[4:5], v[110:111], v[106:107] op_sel_hi:[1,0,1]
	ds_bpermute_b32 v106, v31, v49
	v_pk_fma_f32 v[2:3], v[2:3], v[110:111], v[108:109] op_sel_hi:[1,0,1]
	ds_bpermute_b32 v108, v32, v49
	s_waitcnt vmcnt(13) lgkmcnt(2)
	v_pk_fma_f32 v[4:5], v[60:61], v[116:117], v[4:5] op_sel_hi:[1,0,1]
	v_pk_fma_f32 v[2:3], v[58:59], v[116:117], v[2:3] op_sel_hi:[1,0,1]
	s_waitcnt lgkmcnt(1)
	v_pk_fma_f32 v[8:9], v[60:61], v[106:107], v[112:113] op_sel_hi:[1,0,1]
	ds_bpermute_b32 v60, v32, v48
	v_pk_fma_f32 v[106:107], v[58:59], v[106:107], v[114:115] op_sel_hi:[1,0,1]
	ds_bpermute_b32 v58, v33, v49
	s_waitcnt vmcnt(12) lgkmcnt(2)
	v_pk_fma_f32 v[8:9], v[64:65], v[108:109], v[8:9] op_sel_hi:[1,0,1]
	v_pk_fma_f32 v[106:107], v[62:63], v[108:109], v[106:107] op_sel_hi:[1,0,1]
	s_waitcnt lgkmcnt(1)
	v_pk_fma_f32 v[4:5], v[64:65], v[60:61], v[4:5] op_sel_hi:[1,0,1]
	ds_bpermute_b32 v64, v33, v48
	v_pk_fma_f32 v[2:3], v[62:63], v[60:61], v[2:3] op_sel_hi:[1,0,1]
	ds_bpermute_b32 v60, v34, v49
	s_waitcnt vmcnt(11) lgkmcnt(2)
	v_pk_fma_f32 v[8:9], v[68:69], v[58:59], v[8:9] op_sel_hi:[1,0,1]
	v_pk_fma_f32 v[58:59], v[66:67], v[58:59], v[106:107] op_sel_hi:[1,0,1]
	ds_bpermute_b32 v62, v34, v48
	s_waitcnt lgkmcnt(2)
	v_pk_fma_f32 v[4:5], v[68:69], v[64:65], v[4:5] op_sel_hi:[1,0,1]
	v_pk_fma_f32 v[2:3], v[66:67], v[64:65], v[2:3] op_sel_hi:[1,0,1]
	s_waitcnt vmcnt(10) lgkmcnt(1)
	v_pk_fma_f32 v[8:9], v[72:73], v[60:61], v[8:9] op_sel_hi:[1,0,1]
	ds_bpermute_b32 v64, v35, v49
	v_pk_fma_f32 v[58:59], v[70:71], v[60:61], v[58:59] op_sel_hi:[1,0,1]
	ds_bpermute_b32 v60, v35, v48
	s_waitcnt lgkmcnt(2)
	v_pk_fma_f32 v[4:5], v[72:73], v[62:63], v[4:5] op_sel_hi:[1,0,1]
	v_pk_fma_f32 v[2:3], v[70:71], v[62:63], v[2:3] op_sel_hi:[1,0,1]
	ds_bpermute_b32 v62, v36, v49
	s_waitcnt vmcnt(9) lgkmcnt(2)
	v_pk_fma_f32 v[8:9], v[76:77], v[64:65], v[8:9] op_sel_hi:[1,0,1]
	v_pk_fma_f32 v[58:59], v[74:75], v[64:65], v[58:59] op_sel_hi:[1,0,1]
	s_waitcnt lgkmcnt(1)
	v_pk_fma_f32 v[4:5], v[76:77], v[60:61], v[4:5] op_sel_hi:[1,0,1]
	ds_bpermute_b32 v64, v36, v48
	v_pk_fma_f32 v[2:3], v[74:75], v[60:61], v[2:3] op_sel_hi:[1,0,1]
	ds_bpermute_b32 v60, v37, v49
	s_waitcnt vmcnt(8) lgkmcnt(2)
	v_pk_fma_f32 v[8:9], v[80:81], v[62:63], v[8:9] op_sel_hi:[1,0,1]
	v_pk_fma_f32 v[58:59], v[78:79], v[62:63], v[58:59] op_sel_hi:[1,0,1]
	ds_bpermute_b32 v62, v37, v48
	s_waitcnt lgkmcnt(2)
	v_pk_fma_f32 v[4:5], v[80:81], v[64:65], v[4:5] op_sel_hi:[1,0,1]
	v_pk_fma_f32 v[2:3], v[78:79], v[64:65], v[2:3] op_sel_hi:[1,0,1]
	s_waitcnt vmcnt(7) lgkmcnt(1)
	v_pk_fma_f32 v[8:9], v[84:85], v[60:61], v[8:9] op_sel_hi:[1,0,1]
	ds_bpermute_b32 v64, v38, v49
	v_pk_fma_f32 v[58:59], v[82:83], v[60:61], v[58:59] op_sel_hi:[1,0,1]
	ds_bpermute_b32 v60, v38, v48
	s_waitcnt lgkmcnt(2)
	v_pk_fma_f32 v[4:5], v[84:85], v[62:63], v[4:5] op_sel_hi:[1,0,1]
	v_pk_fma_f32 v[2:3], v[82:83], v[62:63], v[2:3] op_sel_hi:[1,0,1]
	s_waitcnt vmcnt(6) lgkmcnt(1)
	v_pk_fma_f32 v[8:9], v[52:53], v[64:65], v[8:9] op_sel_hi:[1,0,1]
	ds_bpermute_b32 v62, v39, v49
	s_waitcnt lgkmcnt(1)
	v_pk_fma_f32 v[4:5], v[52:53], v[60:61], v[4:5] op_sel_hi:[1,0,1]
	ds_bpermute_b32 v52, v39, v48
	v_pk_fma_f32 v[58:59], v[50:51], v[64:65], v[58:59] op_sel_hi:[1,0,1]
	v_pk_fma_f32 v[2:3], v[50:51], v[60:61], v[2:3] op_sel_hi:[1,0,1]
	ds_bpermute_b32 v50, v40, v49
	s_waitcnt vmcnt(5) lgkmcnt(2)
	v_pk_fma_f32 v[8:9], v[88:89], v[62:63], v[8:9] op_sel_hi:[1,0,1]
	s_waitcnt lgkmcnt(1)
	v_pk_fma_f32 v[4:5], v[88:89], v[52:53], v[4:5] op_sel_hi:[1,0,1]
	v_pk_fma_f32 v[2:3], v[86:87], v[52:53], v[2:3] op_sel_hi:[1,0,1]
	ds_bpermute_b32 v52, v41, v49
	v_pk_fma_f32 v[58:59], v[86:87], v[62:63], v[58:59] op_sel_hi:[1,0,1]
	ds_bpermute_b32 v60, v40, v48
	s_waitcnt vmcnt(4) lgkmcnt(2)
	v_pk_fma_f32 v[8:9], v[92:93], v[50:51], v[8:9] op_sel_hi:[1,0,1]
	v_pk_fma_f32 v[50:51], v[90:91], v[50:51], v[58:59] op_sel_hi:[1,0,1]
	ds_bpermute_b32 v58, v41, v48
	s_waitcnt vmcnt(3) lgkmcnt(2)
	v_pk_fma_f32 v[8:9], v[56:57], v[52:53], v[8:9] op_sel_hi:[1,0,1]
	v_pk_fma_f32 v[50:51], v[54:55], v[52:53], v[50:51] op_sel_hi:[1,0,1]
	ds_bpermute_b32 v52, v42, v48
	s_waitcnt lgkmcnt(2)
	v_pk_fma_f32 v[4:5], v[92:93], v[60:61], v[4:5] op_sel_hi:[1,0,1]
	v_pk_fma_f32 v[2:3], v[90:91], v[60:61], v[2:3] op_sel_hi:[1,0,1]
	ds_bpermute_b32 v60, v42, v49
	s_waitcnt lgkmcnt(2)
	v_pk_fma_f32 v[4:5], v[56:57], v[58:59], v[4:5] op_sel_hi:[1,0,1]
	v_pk_fma_f32 v[2:3], v[54:55], v[58:59], v[2:3] op_sel_hi:[1,0,1]
	ds_bpermute_b32 v54, v43, v49
	s_waitcnt vmcnt(2) lgkmcnt(2)
	v_pk_fma_f32 v[4:5], v[96:97], v[52:53], v[4:5] op_sel_hi:[1,0,1]
	v_pk_fma_f32 v[2:3], v[94:95], v[52:53], v[2:3] op_sel_hi:[1,0,1]
	ds_bpermute_b32 v52, v43, v48
	ds_bpermute_b32 v56, v44, v49
	ds_bpermute_b32 v48, v44, v48
	s_waitcnt lgkmcnt(4)
	v_pk_fma_f32 v[8:9], v[96:97], v[60:61], v[8:9] op_sel_hi:[1,0,1]
	v_pk_fma_f32 v[50:51], v[94:95], v[60:61], v[50:51] op_sel_hi:[1,0,1]
	s_waitcnt vmcnt(1) lgkmcnt(3)
	v_pk_fma_f32 v[8:9], v[100:101], v[54:55], v[8:9] op_sel_hi:[1,0,1]
	v_pk_fma_f32 v[50:51], v[98:99], v[54:55], v[50:51] op_sel_hi:[1,0,1]
	s_waitcnt lgkmcnt(2)
	v_pk_fma_f32 v[54:55], v[100:101], v[52:53], v[4:5] op_sel_hi:[1,0,1]
	v_pk_fma_f32 v[52:53], v[98:99], v[52:53], v[2:3] op_sel_hi:[1,0,1]
	s_waitcnt vmcnt(0) lgkmcnt(1)
	v_pk_fma_f32 v[4:5], v[104:105], v[56:57], v[8:9] op_sel_hi:[1,0,1]
	v_pk_fma_f32 v[2:3], v[102:103], v[56:57], v[50:51] op_sel_hi:[1,0,1]
	s_waitcnt lgkmcnt(0)
	v_pk_fma_f32 v[50:51], v[104:105], v[48:49], v[54:55] op_sel_hi:[1,0,1]
	v_pk_fma_f32 v[48:49], v[102:103], v[48:49], v[52:53] op_sel_hi:[1,0,1]
	ds_write_b128 v45, v[2:5]
	ds_write_b128 v45, v[48:51] offset:1024
	s_waitcnt lgkmcnt(0)
	s_barrier
	ds_read2st64_b32 v[2:3], v10 offset1:8
	ds_read2st64_b32 v[4:5], v10 offset0:16 offset1:24
	ds_read2st64_b32 v[8:9], v10 offset0:32 offset1:40
	s_waitcnt lgkmcnt(2)
	v_add_f32_e32 v2, 0, v2
	v_add_f32_e32 v48, v2, v3
	ds_read2st64_b32 v[2:3], v10 offset0:48 offset1:56
	s_waitcnt lgkmcnt(2)
	v_add_f32_e32 v4, v48, v4
	v_add_f32_e32 v4, v4, v5
	s_waitcnt lgkmcnt(1)
	v_add_f32_e32 v4, v4, v8
	v_add_f32_e32 v4, v4, v9
	s_waitcnt lgkmcnt(0)
	v_add_f32_e32 v2, v4, v2
	v_add_f32_e32 v4, v2, v3
	v_lshl_or_b32 v5, s42, 1, v11
	v_mov_b64_e32 v[2:3], s[20:21]
	v_mad_i64_i32 v[2:3], s[22:23], v5, s40, v[2:3]
	v_lshl_add_u64 v[2:3], s[6:7], 2, v[2:3]
	v_lshl_add_u64 v[2:3], v[2:3], 0, v[6:7]
	flat_store_dword v[2:3], v4 sc1
	s_waitcnt lgkmcnt(0)
	s_barrier
	s_cbranch_scc1 .LBB0_23

.LBB0_23:
	s_waitcnt vmcnt(0) lgkmcnt(0)
	s_barrier
	v_cmp_eq_u32_e32 vcc, 0, v0
	s_and_saveexec_b64 s[46:47], vcc
	s_cbranch_execz .Lp0_arrived
	v_mov_b32_e32 v200, 0x6200
	v_mov_b32_e32 v201, 1
	global_atomic_add v200, v201, s[24:25]
.Lp0_arrived:
	s_or_b64 exec, exec, s[46:47]
	s_lshl_b32 s20, s3, 3
	s_cmpk_lg_i32 s3, 0x100
	s_cselect_b64 s[6:7], -1, 0
	s_and_b64 s[4:5], s[6:7], exec
	s_cselect_b32 s4, 0, 0xfffff400
	s_abs_i32 s5, s20
	v_cvt_f32_u32_e32 v2, s5
	s_add_i32 s4, s20, s4
	s_waitcnt lgkmcnt(0)
	s_add_i32 s9, s4, 0x1dff
	s_sub_i32 s4, 0xffffe201, s4
	v_rcp_iflag_f32_e32 v2, v2
	s_xor_b32 s16, s9, s20
	s_sub_i32 s8, 0, s5
	s_max_i32 s4, s9, s4
	v_mul_f32_e32 v2, 0x4f7ffffe, v2
	v_cvt_u32_f32_e32 v2, v2
	s_ashr_i32 s9, s16, 31
	v_or_b32_e32 v10, s31, v0
	v_readfirstlane_b32 s16, v2
	s_mul_i32 s8, s8, s16
	s_mul_hi_u32 s8, s16, s8
	s_add_i32 s16, s16, s8
	s_mul_hi_u32 s8, s4, s16
	s_mul_i32 s16, s8, s5
	s_sub_i32 s4, s4, s16
	s_add_i32 s16, s8, 1
	s_sub_i32 s17, s4, s5
	s_cmp_ge_u32 s4, s5
	s_cselect_b32 s8, s16, s8
	s_cselect_b32 s4, s17, s4
	s_add_i32 s16, s8, 1
	s_cmp_ge_u32 s4, s5
	s_cselect_b32 s4, s16, s8
	s_xor_b32 s4, s4, s9
	s_sub_i32 s4, s4, s9
	s_cmp_lt_i32 s4, -2
	s_mov_b32 s5, 0
	s_cbranch_scc1 .LBB0_46
	s_ashr_i32 s23, s2, 31
	s_lshr_b32 s23, s23, 29
	s_add_i32 s23, s2, s23
	s_and_b32 s31, s23, 0x1ffffff8
	s_lshr_b32 s22, s3, 3
	s_sub_i32 s31, s2, s31
	s_mul_i32 s22, s22, s31
	s_lshr_b32 s23, s23, 3
	s_add_i32 s31, s22, s23
	s_lshl_b32 s22, s28, 14
	s_and_b32 s21, s3, 7
	s_add_i32 s34, s22, 0
	s_load_dwordx2 s[8:9], s[0:1], 0x30
	s_load_dwordx2 s[16:17], s[0:1], 0x80
	s_and_b64 s[22:23], s[6:7], exec
	s_cselect_b32 s22, 0, 0xc00
	s_lshl_b32 s23, s2, 3
	s_add_i32 s23, s28, s23
	s_nor_b64 s[6:7], s[18:19], s[6:7]
	s_add_i32 s18, s23, 0xfffffc00
	v_and_b32_e32 v4, 7, v1
	s_cmp_eq_u32 s21, 0
	v_lshlrev_b32_e32 v6, 4, v4
	v_mov_b32_e32 v7, 0
	s_cselect_b32 s19, s31, s2
	v_ashrrev_i32_e32 v11, 3, v1
	s_waitcnt lgkmcnt(0)
	v_lshl_add_u64 v[2:3], s[16:17], 0, v[6:7]
	s_movk_i32 s16, 0x84
	s_add_i32 s4, s4, 2
	s_lshl_b32 s21, s19, 3
	v_add_u32_e32 v15, s34, v6
	v_mul_lo_u32 v16, v11, s16
	v_lshl_add_u64 v[8:9], s[14:15], 0, v[6:7]
	s_mov_b64 s[16:17], 0x2600000
	v_lshl_add_u64 v[6:7], s[8:9], 0, v[6:7]
	s_mov_b64 s[8:9], 0x200000
	s_max_i32 s19, s4, 0
	s_add_i32 s4, s22, s28
	v_mul_u32_u24_e32 v14, 0x420, v4
	v_lshl_add_u64 v[4:5], v[8:9], 0, s[16:17]
	v_lshlrev_b32_e32 v17, 2, v11
	v_lshl_add_u64 v[8:9], v[8:9], 0, s[8:9]
	s_add_i32 s4, s4, s21
	s_mul_i32 s8, s3, 24
	v_add_u32_e32 v15, v15, v16
	v_add_u32_e32 v1, 8, v11
	v_add_u32_e32 v12, 16, v11
	v_add_u32_e32 v13, 24, v11
	v_add3_u32 v14, s34, v14, v17
	s_add_i32 s19, s19, 1
	s_sub_i32 s21, s4, s8
	v_add_u32_e32 v16, 0x420, v15
	v_add_u32_e32 v17, 0x428, v15
	v_add_u32_e32 v18, 0x840, v15
	v_add_u32_e32 v19, 0x848, v15
	v_add_u32_e32 v20, 0xc60, v15
	v_add_u32_e32 v21, 0xc68, v15
	v_add_u32_e32 v22, 0x1080, v15
	v_add_u32_e32 v23, 0x1088, v15
	v_add_u32_e32 v24, 0x14a0, v15
	v_add_u32_e32 v25, 0x14a8, v15
	v_add_u32_e32 v26, 0x18c0, v15
	v_add_u32_e32 v27, 0x18c8, v15
	v_add_u32_e32 v28, 0x1ce0, v15
	v_add_u32_e32 v29, 0x1ce8, v15
	s_movk_i32 s22, 0x7000
	s_mov_b32 s23, 0
	s_branch .LBB0_26

.LBB0_68:
	s_cmp_gt_i32 s27, 1
	s_cselect_b64 s[4:5], -1, 0
	s_and_b64 s[6:7], s[12:13], s[4:5]
	s_andn2_b64 vcc, exec, s[6:7]
	s_cbranch_vccnz .LBB0_118
	v_cmp_eq_u32_e32 vcc, 0, v0
	s_and_saveexec_b64 s[6:7], vcc
	s_cbranch_execz .LBB0_117
	v_mov_b32_e32 v1, 0x6200
	s_mov_b32 s8, 0
.Lp1_spin:
	global_load_dword v2, v1, s[24:25] sc1
	s_waitcnt vmcnt(0)
	v_readfirstlane_b32 s9, v2
	s_nop 0
	s_cmpk_gt_u32 s9, 0xff
	s_cbranch_scc1 .LBB0_117
	s_sleep 1
	s_add_i32 s8, s8, 1
	s_cmp_lt_u32 s8, 0x20000
	s_cbranch_scc1 .Lp1_spin

.LBB0_121:
	s_ashr_i32 s4, s54, 31
	s_lshr_b32 s4, s4, 25
	s_add_i32 s4, s54, s4
	s_ashr_i32 s44, s4, 7
	s_mul_i32 s45, s44, 0x6000
	s_mul_hi_i32 s4, s44, 0x6000
	s_add_u32 s10, s49, s45
	s_addc_u32 s11, s50, s4
	s_add_u32 s14, s10, 0x2000
	s_addc_u32 s15, s11, 0
	s_add_i32 s4, s44, 2
	s_add_i32 s5, s45, 0xc000
	s_mul_hi_i32 s4, s4, 0x6000
	s_add_u32 s16, s49, s5
	s_addc_u32 s17, s50, s4
	s_add_u32 s18, s16, 0x2000
	s_addc_u32 s19, s17, 0
	s_add_i32 s4, s44, 4
	s_add_i32 s5, s45, 0x18000
	s_mul_hi_i32 s8, s4, 0x6000
	s_add_u32 s4, s49, s5
	s_addc_u32 s5, s50, s8
	s_add_u32 s8, s4, 0x2000
	s_addc_u32 s9, s5, 0
	s_add_i32 s20, s44, 6
	s_add_i32 s21, s45, 0x24000
	s_mul_hi_i32 s22, s20, 0x6000
	s_add_u32 s20, s49, s21
	s_addc_u32 s21, s50, s22
	s_add_u32 s22, s20, 0x2000
	s_addc_u32 s23, s21, 0
	s_add_i32 s30, s44, 8
	s_add_i32 s31, s45, 0x30000
	s_mul_hi_i32 s34, s30, 0x6000
	s_add_u32 s30, s49, s31
	s_addc_u32 s31, s50, s34
	s_add_u32 s34, s30, 0x2000
	s_addc_u32 s35, s31, 0
	s_add_i32 s36, s44, 10
	s_add_i32 s37, s45, 0x3c000
	s_mul_hi_i32 s38, s36, 0x6000
	s_add_u32 s36, s49, s37
	s_addc_u32 s37, s50, s38
	s_add_u32 s38, s36, 0x2000
	s_addc_u32 s39, s37, 0
	s_add_i32 s40, s44, 12
	s_add_i32 s41, s45, 0x48000
	s_mul_hi_i32 s42, s40, 0x6000
	s_add_u32 s40, s49, s41
	s_addc_u32 s41, s50, s42
	v_lshl_add_u64 v[2:3], s[10:11], 0, v[14:15]
	v_lshl_add_u64 v[4:5], s[14:15], 0, v[14:15]
	v_lshl_add_u64 v[6:7], s[16:17], 0, v[14:15]
	v_lshl_add_u64 v[38:39], s[18:19], 0, v[14:15]
	v_lshl_add_u64 v[8:9], s[4:5], 0, v[14:15]
	flat_load_dword v71, v[16:17] sc1
	flat_load_dword v72, v[18:19] sc1
	flat_load_dword v73, v[2:3] sc1
	flat_load_dword v74, v[4:5] sc1
	flat_load_dword v75, v[6:7] sc1
	flat_load_dword v76, v[38:39] sc1
	flat_load_dword v77, v[8:9] sc1
	s_add_u32 s42, s40, 0x2000
	s_addc_u32 s43, s41, 0
	s_add_i32 s44, s44, 14
	s_add_i32 s45, s45, 0x54000
	s_mul_hi_i32 s46, s44, 0x6000
	s_add_u32 s44, s49, s45
	v_lshl_add_u64 v[60:61], s[8:9], 0, v[14:15]
	s_addc_u32 s45, s50, s46
	v_lshl_add_u64 v[58:59], s[20:21], 0, v[14:15]
	v_lshl_add_u64 v[56:57], s[22:23], 0, v[14:15]
	v_lshl_add_u64 v[54:55], s[30:31], 0, v[14:15]
	v_lshl_add_u64 v[52:53], s[34:35], 0, v[14:15]
	v_lshl_add_u64 v[50:51], s[36:37], 0, v[14:15]
	v_lshl_add_u64 v[48:49], s[38:39], 0, v[14:15]
	v_lshl_add_u64 v[46:47], s[40:41], 0, v[14:15]
	flat_load_dword v78, v[60:61] sc1
	flat_load_dword v79, v[58:59] sc1
	flat_load_dword v80, v[56:57] sc1
	flat_load_dword v81, v[54:55] sc1
	flat_load_dword v82, v[52:53] sc1
	flat_load_dword v83, v[50:51] sc1
	flat_load_dword v84, v[48:49] sc1
	flat_load_dword v85, v[46:47] sc1
	v_lshl_add_u64 v[44:45], s[42:43], 0, v[14:15]
	s_add_u32 s46, s44, 0x2000
	v_lshl_add_u64 v[42:43], s[44:45], 0, v[14:15]
	flat_load_dword v86, v[44:45] sc1
	flat_load_dword v87, v[42:43] sc1
	s_addc_u32 s47, s45, 0
	v_lshl_add_u64 v[40:41], s[46:47], 0, v[14:15]
	flat_load_dword v88, v[40:41] sc1
	flat_load_dword v89, v[20:21] sc1
	v_lshl_add_u64 v[90:91], s[34:35], 0, v[36:37]
	v_lshl_add_u64 v[92:93], s[36:37], 0, v[36:37]
	v_lshl_add_u64 v[94:95], s[38:39], 0, v[36:37]
	v_lshl_add_u64 v[96:97], s[40:41], 0, v[36:37]
	v_lshl_add_u64 v[98:99], s[42:43], 0, v[36:37]
	v_lshl_add_u64 v[100:101], s[44:45], 0, v[36:37]
	v_lshl_add_u64 v[102:103], s[46:47], 0, v[36:37]
	s_waitcnt vmcnt(0) lgkmcnt(0)
	v_add_f32_e32 v71, v71, v73
	v_add_f32_e32 v72, v72, v74
	v_add_f32_e32 v71, v71, v75
	v_add_f32_e32 v72, v72, v76
	v_add_f32_e32 v71, v71, v77
	v_lshl_add_u64 v[74:75], s[14:15], 0, v[36:37]
	v_lshl_add_u64 v[76:77], s[16:17], 0, v[36:37]
	v_add_f32_e32 v72, v72, v78
	v_add_f32_e32 v71, v71, v79
	v_add_f32_e32 v72, v72, v80
	v_add_f32_e32 v71, v71, v81
	v_add_f32_e32 v72, v72, v82
	v_add_f32_e32 v71, v71, v83
	v_add_f32_e32 v72, v72, v84
	v_add_f32_e32 v71, v71, v85
	v_lshl_add_u64 v[78:79], s[18:19], 0, v[36:37]
	v_lshl_add_u64 v[80:81], s[4:5], 0, v[36:37]
	v_add_f32_e32 v72, v72, v86
	v_add_f32_e32 v71, v71, v87
	ds_write_b32 v68, v71 offset:8192
	v_add_f32_e32 v71, v72, v88
	v_add_f32_e32 v71, 1.0, v71
	v_mul_f32_e32 v71, v71, v89
	ds_write_b32 v68, v71
	flat_load_dword v71, v[16:17] offset:2048 sc1
	flat_load_dword v104, v[22:23] sc1
	flat_load_dword v105, v[2:3] offset:2048 sc1
	flat_load_dword v106, v[4:5] offset:2048 sc1
	flat_load_dword v107, v[6:7] offset:2048 sc1
	flat_load_dword v108, v[38:39] offset:2048 sc1
	flat_load_dword v109, v[8:9] offset:2048 sc1
	flat_load_dword v110, v[60:61] offset:2048 sc1
	flat_load_dword v111, v[58:59] offset:2048 sc1
	flat_load_dword v112, v[56:57] offset:2048 sc1
	flat_load_dword v113, v[54:55] offset:2048 sc1
	flat_load_dword v114, v[52:53] offset:2048 sc1
	flat_load_dword v115, v[50:51] offset:2048 sc1
	flat_load_dword v116, v[48:49] offset:2048 sc1
	flat_load_dword v117, v[46:47] offset:2048 sc1
	flat_load_dword v118, v[44:45] offset:2048 sc1
	flat_load_dword v119, v[42:43] offset:2048 sc1
	flat_load_dword v120, v[40:41] offset:2048 sc1
	flat_load_dword v121, v[20:21] offset:2048 sc1
	v_lshl_add_u64 v[72:73], s[10:11], 0, v[36:37]
	v_lshl_add_u64 v[82:83], s[8:9], 0, v[36:37]
	v_lshl_add_u64 v[84:85], s[20:21], 0, v[36:37]
	v_lshl_add_u64 v[86:87], s[22:23], 0, v[36:37]
	v_lshl_add_u64 v[88:89], s[30:31], 0, v[36:37]
	s_waitcnt vmcnt(0) lgkmcnt(0)
	v_add_f32_e32 v71, v71, v105
	v_add_f32_e32 v104, v104, v106
	v_add_f32_e32 v71, v71, v107
	v_add_f32_e32 v104, v104, v108
	v_add_f32_e32 v71, v71, v109
	v_add_f32_e32 v104, v104, v110
	v_add_f32_e32 v71, v71, v111
	v_add_f32_e32 v104, v104, v112
	v_add_f32_e32 v71, v71, v113
	v_add_f32_e32 v104, v104, v114
	v_add_f32_e32 v71, v71, v115
	v_add_f32_e32 v104, v104, v116
	v_add_f32_e32 v71, v71, v117
	v_add_f32_e32 v104, v104, v118
	v_add_f32_e32 v71, v71, v119
	v_add_f32_e32 v104, v104, v120
	v_add_f32_e32 v104, 1.0, v104
	ds_write_b32 v68, v71 offset:10240
	v_mul_f32_e32 v71, v104, v121
	ds_write_b32 v68, v71 offset:2048
	flat_load_dword v71, v[72:73] sc1
	s_nop 0
	flat_load_dword v72, v[74:75] sc1
	flat_load_dword v73, v[24:25] sc1
	flat_load_dword v104, v[26:27] sc1
	flat_load_dword v105, v[76:77] sc1
	flat_load_dword v106, v[78:79] sc1
	flat_load_dword v107, v[80:81] sc1
	flat_load_dword v108, v[82:83] sc1
	flat_load_dword v109, v[84:85] sc1
	flat_load_dword v110, v[86:87] sc1
	flat_load_dword v111, v[88:89] sc1
	flat_load_dword v112, v[90:91] sc1
	flat_load_dword v113, v[92:93] sc1
	flat_load_dword v114, v[94:95] sc1
	flat_load_dword v115, v[96:97] sc1
	flat_load_dword v116, v[98:99] sc1
	flat_load_dword v74, v[100:101] sc1
	flat_load_dword v75, v[102:103] sc1
	flat_load_dword v76, v[28:29] sc1
	s_waitcnt vmcnt(0) lgkmcnt(0)
	v_add_f32_e32 v71, v73, v71
	v_add_f32_e32 v72, v104, v72
	v_add_f32_e32 v71, v71, v105
	v_add_f32_e32 v72, v72, v106
	v_add_f32_e32 v71, v71, v107
	v_add_f32_e32 v72, v72, v108
	v_add_f32_e32 v71, v71, v109
	v_add_f32_e32 v72, v72, v110
	v_add_f32_e32 v71, v71, v111
	v_add_f32_e32 v72, v72, v112
	v_add_f32_e32 v71, v71, v113
	v_add_f32_e32 v72, v72, v114
	v_add_f32_e32 v71, v71, v115
	v_add_f32_e32 v72, v72, v116
	v_add_f32_e32 v71, v71, v74
	v_add_f32_e32 v72, v72, v75
	v_add_f32_e32 v72, 1.0, v72
	v_mul_f32_e32 v72, v72, v76
	ds_write_b32 v68, v72 offset:4096
	ds_write_b32 v68, v71 offset:12288
	s_and_saveexec_b64 s[4:5], s[6:7]
	s_cbranch_execz .LBB0_123
	v_add_co_u32_e32 v2, vcc, 0x1000, v2
	s_nop 1
	v_addc_co_u32_e32 v3, vcc, 0, v3, vcc
	v_add_co_u32_e32 v4, vcc, 0x1000, v4
	s_nop 1
	v_addc_co_u32_e32 v5, vcc, 0, v5, vcc
	v_add_co_u32_e32 v6, vcc, 0x1000, v6
	s_nop 1
	v_addc_co_u32_e32 v7, vcc, 0, v7, vcc
	v_add_co_u32_e32 v38, vcc, 0x1000, v38
	s_nop 1
	v_addc_co_u32_e32 v39, vcc, 0, v39, vcc
	v_add_co_u32_e32 v8, vcc, 0x1000, v8
	s_nop 1
	v_addc_co_u32_e32 v9, vcc, 0, v9, vcc
	flat_load_dword v71, v[30:31] sc1
	flat_load_dword v72, v[32:33] sc1
	flat_load_dword v73, v[2:3] offset:2048 sc1
	flat_load_dword v74, v[4:5] offset:2048 sc1
	flat_load_dword v75, v[6:7] offset:2048 sc1
	flat_load_dword v76, v[38:39] offset:2048 sc1
	flat_load_dword v77, v[8:9] offset:2048 sc1
	v_add_co_u32_e32 v2, vcc, 0x1000, v60
	s_nop 1
	v_addc_co_u32_e32 v3, vcc, 0, v61, vcc
	v_add_co_u32_e32 v4, vcc, 0x1000, v58
	s_nop 1
	v_addc_co_u32_e32 v5, vcc, 0, v59, vcc
	v_add_co_u32_e32 v6, vcc, 0x1000, v56
	s_nop 1
	v_addc_co_u32_e32 v7, vcc, 0, v57, vcc
	v_add_co_u32_e32 v8, vcc, 0x1000, v54
	s_nop 1
	v_addc_co_u32_e32 v9, vcc, 0, v55, vcc
	v_add_co_u32_e32 v38, vcc, 0x1000, v52
	s_nop 1
	v_addc_co_u32_e32 v39, vcc, 0, v53, vcc
	v_add_co_u32_e32 v50, vcc, 0x1000, v50
	s_nop 1
	v_addc_co_u32_e32 v51, vcc, 0, v51, vcc
	v_add_co_u32_e32 v48, vcc, 0x1000, v48
	s_nop 1
	v_addc_co_u32_e32 v49, vcc, 0, v49, vcc
	v_add_co_u32_e32 v46, vcc, 0x1000, v46
	s_nop 1
	v_addc_co_u32_e32 v47, vcc, 0, v47, vcc
	flat_load_dword v52, v[2:3] offset:2048 sc1
	flat_load_dword v53, v[4:5] offset:2048 sc1
	flat_load_dword v54, v[6:7] offset:2048 sc1
	flat_load_dword v55, v[8:9] offset:2048 sc1
	flat_load_dword v56, v[38:39] offset:2048 sc1
	flat_load_dword v57, v[50:51] offset:2048 sc1
	flat_load_dword v58, v[48:49] offset:2048 sc1
	flat_load_dword v59, v[46:47] offset:2048 sc1
	v_add_co_u32_e32 v2, vcc, 0x1000, v44
	s_nop 1
	v_addc_co_u32_e32 v3, vcc, 0, v45, vcc
	v_add_co_u32_e32 v4, vcc, 0x1000, v42
	s_nop 1
	v_addc_co_u32_e32 v5, vcc, 0, v43, vcc
	v_add_co_u32_e32 v6, vcc, 0x1000, v40
	s_nop 1
	v_addc_co_u32_e32 v7, vcc, 0, v41, vcc
	flat_load_dword v8, v[2:3] offset:2048 sc1
	flat_load_dword v9, v[4:5] offset:2048 sc1
	flat_load_dword v38, v[6:7] offset:2048 sc1
	flat_load_dword v39, v[34:35] sc1
	s_waitcnt vmcnt(0) lgkmcnt(0)
	v_add_f32_e32 v2, v71, v73
	v_add_f32_e32 v3, v72, v74
	v_add_f32_e32 v2, v2, v75
	v_add_f32_e32 v3, v3, v76
	v_add_f32_e32 v2, v2, v77
	v_add_f32_e32 v3, v3, v52
	v_add_f32_e32 v2, v2, v53
	v_add_f32_e32 v3, v3, v54
	v_add_f32_e32 v2, v2, v55
	v_add_f32_e32 v3, v3, v56
	v_add_f32_e32 v2, v2, v57
	v_add_f32_e32 v3, v3, v58
	v_add_f32_e32 v2, v2, v59
	v_add_f32_e32 v3, v3, v8
	v_add_f32_e32 v2, v2, v9
	v_add_f32_e32 v3, v3, v38
	v_add_f32_e32 v3, 1.0, v3
	v_mul_f32_e32 v3, v3, v39
	ds_write2st64_b32 v68, v3, v2 offset0:24 offset1:56
